# attention: next-unit ticket atomic issued at the unit's epilogue start and resolved at the unit end (no ticket wait at the unit head, one unit of queue commitment instead of two)
# speedup vs baseline: 1.0440x; 1.0041x over previous
.LBB0_318:
	s_lshr_b32 s6, s88, 4
	s_and_b32 s59, s6, 8
	s_not_b32 s6, s88
	s_lshl_b32 s6, s6, 5
	s_and_b32 s8, s6, 0xf00
	s_add_i32 s6, s8, 0x100
	v_mov_b32_e32 v34, v208
	s_lshr_b32 s60, s6, 6
	s_and_b32 s61, s88, 7
	s_lshr_b32 s10, s88, 8
	s_add_i32 s54, s60, -4
	v_and_b32_e32 v204, 63, v34
	s_or_b32 s58, s59, s61
	v_readfirstlane_b32 s56, v34
	s_mov_b32 s9, s11
	s_lshl_b32 s63, s10, 4
	s_lshl_b64 s[98:99], s[10:11], 12
	s_or_b64 s[98:99], s[98:99], s[8:9]
	s_lshr_b32 s101, s56, 6
	s_lshl_b32 s101, s101, 5
	s_add_u32 s98, s98, s101
	s_addc_u32 s99, s99, 0
	s_lshl_b64 s[98:99], s[98:99], 11
	s_add_u32 s98, s69, s98
	s_addc_u32 s99, s70, s99
	s_lshl_b32 s101, s58, 7
	s_add_u32 s98, s98, s101
	s_addc_u32 s99, s99, 0
	v_and_b32_e32 v112, 31, v34
	v_lshlrev_b32_e32 v112, 11, v112
	v_lshrrev_b32_e32 v113, 5, v204
	v_lshl_or_b32 v112, v113, 4, v112
	global_load_dwordx4 v[124:127], v112, s[98:99]
	global_load_dwordx4 v[120:123], v112, s[98:99] offset:32
	global_load_dwordx4 v[116:119], v112, s[98:99] offset:64
	global_load_dwordx4 v[112:115], v112, s[98:99] offset:96
	v_cmp_gt_u32_e32 vcc, s54, v204
	s_mov_b64 s[52:53], 0
	s_and_saveexec_b64 s[6:7], vcc
	s_cbranch_execz .LBB0_354
	s_or_b32 s52, s58, s63
	s_mov_b32 s53, s11
	s_lshl_b64 s[52:53], s[52:53], 14
	s_add_u32 s52, s77, s52
	s_addc_u32 s53, s78, s53
	s_lshl_b32 s55, s8, 2
	v_lshlrev_b32_e32 v0, 8, v204
	v_mov_b32_e32 v2, s55
	global_load_dword v2, v2, s[52:53]
	s_nop 0
	global_load_dword v0, v0, s[52:53] offset:252
	s_waitcnt vmcnt(0)
	v_sub_f32_e32 v0, v2, v0
	v_cmp_gt_f32_e32 vcc, v0, v201
	s_and_b64 s[52:53], vcc, exec

.LBB0_380:
	v_add_f32_e32 v2, v64, v65
	v_add_f32_e32 v2, v66, v2
	v_add_f32_e32 v2, v67, v2
	v_add_f32_e32 v2, v68, v2
	v_add_f32_e32 v2, v69, v2
	v_add_f32_e32 v2, v70, v2
	v_add_f32_e32 v2, v71, v2
	v_add_f32_e32 v2, v72, v2
	v_add_f32_e32 v2, v73, v2
	v_add_f32_e32 v2, v74, v2
	v_add_f32_e32 v2, v75, v2
	v_add_f32_e32 v2, v76, v2
	v_add_f32_e32 v2, v77, v2
	v_add_f32_e32 v2, v78, v2
	v_add_f32_e32 v2, v79, v2
	v_add_f32_e32 v2, v48, v2
	v_add_f32_e32 v2, v49, v2
	v_add_f32_e32 v2, v50, v2
	v_add_f32_e32 v2, v51, v2
	v_add_f32_e32 v2, v52, v2
	v_add_f32_e32 v2, v53, v2
	v_add_f32_e32 v2, v54, v2
	v_add_f32_e32 v2, v55, v2
	v_add_f32_e32 v2, v56, v2
	v_add_f32_e32 v2, v57, v2
	v_add_f32_e32 v2, v58, v2
	v_add_f32_e32 v2, v59, v2
	v_add_f32_e32 v2, v60, v2
	v_add_f32_e32 v2, v61, v2
	s_cmp_lg_u32 0, -1
	v_add_f32_e32 v2, v62, v2
	s_cselect_b32 s6, 0, 0
	v_add_f32_e32 v2, v63, v2
	s_addk_i32 s6, 0x6000
	v_add_f32_e32 v0, v0, v2
	v_cvt_pk_bf16_f32 v2, v64, v65
	v_add3_u32 v14, v212, s6, v209
	v_cvt_pk_bf16_f32 v3, v66, v67
	v_cvt_pk_bf16_f32 v4, v68, v69
	v_cvt_pk_bf16_f32 v5, v70, v71
	v_cvt_pk_bf16_f32 v6, v72, v73
	v_cvt_pk_bf16_f32 v7, v74, v75
	v_cvt_pk_bf16_f32 v8, v76, v77
	v_cvt_pk_bf16_f32 v9, v78, v79
	v_cvt_pk_bf16_f32 v10, v48, v49
	v_cvt_pk_bf16_f32 v11, v50, v51
	v_cvt_pk_bf16_f32 v12, v52, v53
	v_cvt_pk_bf16_f32 v13, v54, v55
	v_cvt_pk_bf16_f32 v48, v56, v57
	v_cvt_pk_bf16_f32 v49, v58, v59
	v_cvt_pk_bf16_f32 v50, v60, v61
	v_cvt_pk_bf16_f32 v51, v62, v63
	v_add3_u32 v14, v14, v211, s67
	ds_read_b64_tr_b16 v[52:53],v14 offset:0
	ds_read_b64_tr_b16 v[54:55],v14 offset:512
	ds_read_b64_tr_b16 v[56:57],v14 offset:1024
	ds_read_b64_tr_b16 v[58:59],v14 offset:1536
	ds_read_b64_tr_b16 v[60:61],v14 offset:2048
	ds_read_b64_tr_b16 v[62:63],v14 offset:2560
	ds_read_b64_tr_b16 v[64:65],v14 offset:3072
	ds_read_b64_tr_b16 v[66:67],v14 offset:3584
	s_waitcnt lgkmcnt(0)
	s_nop 0
	v_mfma_f32_32x32x16_bf16 v[32:47], v[2:5], v[52:55], v[32:47]
	ds_read_b64_tr_b16 v[52:53],v14 offset:4096
	ds_read_b64_tr_b16 v[54:55],v14 offset:4608
	v_mfma_f32_32x32x16_bf16 v[32:47], v[6:9], v[56:59], v[32:47]
	ds_read_b64_tr_b16 v[56:57],v14 offset:5120
	ds_read_b64_tr_b16 v[58:59],v14 offset:5632
	v_mfma_f32_32x32x16_bf16 v[32:47], v[10:13], v[60:63], v[32:47]
	ds_read_b64_tr_b16 v[60:61],v14 offset:6144
	ds_read_b64_tr_b16 v[62:63],v14 offset:6656
	ds_read_b64_tr_b16 v[68:69],v14 offset:7168
	ds_read_b64_tr_b16 v[70:71],v14 offset:7680
	s_waitcnt lgkmcnt(0)
	v_mfma_f32_32x32x16_bf16 v[32:47], v[48:51], v[64:67], v[32:47]
	v_mfma_f32_32x32x16_bf16 v[16:31], v[2:5], v[52:55], v[16:31]
	v_mov_b32_e32 v2, v0
	s_nop 1
	v_permlane32_swap_b32_e32 v0, v2
	v_cmp_gt_u32_e32 vcc, 32, v204
	v_mfma_f32_32x32x16_bf16 v[16:31], v[6:9], v[56:59], v[16:31]
	v_mfma_f32_32x32x16_bf16 v[16:31], v[10:13], v[60:63], v[16:31]
	v_mfma_f32_32x32x16_bf16 v[16:31], v[48:51], v[68:71], v[16:31]
	s_and_saveexec_b64 s[6:7], vcc
	v_add_f32_e32 v0, v0, v2
	ds_write_b32 v214, v0 offset:49280
	s_or_b64 exec, exec, s[6:7]
	s_and_saveexec_b64 s[98:99], s[26:27]
	s_cbranch_execz .Lattn_tk_skip
	v_mov_b32_e32 v203, 1
	global_atomic_add v203, v1, v203, s[12:13] sc0
.Lattn_tk_skip:
	s_or_b64 exec, exec, s[98:99]
	s_waitcnt lgkmcnt(0)
	ds_read_b128 v[2:5], v213 offset:49280
	ds_read_b128 v[6:9], v213 offset:49312
	s_lshl_b64 s[6:7], s[52:53], 1
	s_add_u32 s6, s75, s6
	s_addc_u32 s7, s76, s7
	s_waitcnt lgkmcnt(1)
	v_rcp_f32_e32 v0, v2
	v_rcp_f32_e32 v10, v3
	s_lshl_b32 s8, s62, 12
	s_add_i32 s8, s8, 0
	v_lshlrev_b32_e32 v49, 1, v206
	v_lshlrev_b32_e32 v50, 9, v207
	v_mul_f32_e32 v32, v32, v0
	v_mul_f32_e32 v0, v16, v0
	v_add3_u32 v49, s8, v49, v50
	v_cvt_pk_bf16_f32 v0, v0, s0
	v_rcp_f32_e32 v11, v4
	v_rcp_f32_e32 v12, v5
	s_waitcnt lgkmcnt(0)
	v_rcp_f32_e32 v13, v6
	ds_read_b128 v[2:5], v213 offset:49344
	v_rcp_f32_e32 v14, v7
	v_rcp_f32_e32 v15, v8
	v_rcp_f32_e32 v48, v9
	ds_read_b128 v[6:9], v213 offset:49376
	ds_write_b16 v49, v0 offset:51264
	v_mul_f32_e32 v0, v33, v10
	v_cvt_pk_bf16_f32 v0, v0, s0
	ds_write_b16 v49, v0 offset:51328
	v_mul_f32_e32 v0, v17, v10
	v_cvt_pk_bf16_f32 v0, v0, s0
	ds_write_b16 v49, v0 offset:51392
	v_mul_f32_e32 v0, v34, v11
	v_cvt_pk_bf16_f32 v0, v0, s0
	ds_write_b16 v49, v0 offset:51456
	v_mul_f32_e32 v0, v18, v11
	v_cvt_pk_bf16_f32 v0, v0, s0
	ds_write_b16 v49, v0 offset:51520
	v_mul_f32_e32 v0, v35, v12
	v_cvt_pk_bf16_f32 v0, v0, s0
	ds_write_b16 v49, v0 offset:51584
	v_mul_f32_e32 v0, v19, v12
	v_cvt_pk_bf16_f32 v0, v0, s0
	ds_write_b16 v49, v0 offset:51648
	v_mul_f32_e32 v0, v36, v13
	v_cvt_pk_bf16_f32 v0, v0, s0
	ds_write_b16 v49, v0 offset:52224
	v_mul_f32_e32 v0, v20, v13
	v_cvt_pk_bf16_f32 v0, v0, s0
	ds_write_b16 v49, v0 offset:52288
	v_mul_f32_e32 v0, v37, v14
	v_cvt_pk_bf16_f32 v0, v0, s0
	ds_write_b16 v49, v0 offset:52352
	v_mul_f32_e32 v0, v21, v14
	v_cvt_pk_bf16_f32 v0, v0, s0
	ds_write_b16 v49, v0 offset:52416
	v_mul_f32_e32 v0, v38, v15
	v_cvt_pk_bf16_f32 v0, v0, s0
	ds_write_b16 v49, v0 offset:52480
	v_mul_f32_e32 v0, v22, v15
	v_cvt_pk_bf16_f32 v0, v0, s0
	s_waitcnt lgkmcnt(13)
	v_rcp_f32_e32 v2, v2
	ds_write_b16 v49, v0 offset:52544
	v_mul_f32_e32 v0, v39, v48
	v_cvt_pk_bf16_f32 v0, v0, s0
	ds_write_b16 v49, v0 offset:52608
	v_mul_f32_e32 v0, v23, v48
	v_cvt_pk_bf16_f32 v0, v0, s0
	v_rcp_f32_e32 v3, v3
	ds_write_b16 v49, v0 offset:52672
	v_mul_f32_e32 v0, v40, v2
	v_cvt_pk_bf16_f32 v0, v0, s0
	ds_write_b16 v49, v0 offset:53248
	v_mul_f32_e32 v0, v24, v2
	v_cvt_pk_bf16_f32 v0, v0, s0
	v_rcp_f32_e32 v4, v4
	ds_write_b16 v49, v0 offset:53312
	v_mul_f32_e32 v0, v41, v3
	v_cvt_pk_bf16_f32 v0, v0, s0
	ds_write_b16 v49, v0 offset:53376
	v_mul_f32_e32 v0, v25, v3
	v_cvt_pk_bf16_f32 v0, v0, s0
	v_rcp_f32_e32 v5, v5
	ds_write_b16 v49, v0 offset:53440
	v_mul_f32_e32 v0, v42, v4
	v_cvt_pk_bf16_f32 v0, v0, s0
	ds_write_b16 v49, v0 offset:53504
	v_mul_f32_e32 v0, v26, v4
	v_cvt_pk_bf16_f32 v0, v0, s0
	s_waitcnt lgkmcnt(14)
	v_rcp_f32_e32 v6, v6
	ds_write_b16 v49, v0 offset:53568
	v_mul_f32_e32 v0, v43, v5
	v_cvt_pk_bf16_f32 v0, v0, s0
	ds_write_b16 v49, v0 offset:53632
	v_mul_f32_e32 v0, v27, v5
	v_cvt_pk_bf16_f32 v0, v0, s0
	v_rcp_f32_e32 v7, v7
	ds_write_b16 v49, v0 offset:53696
	v_mul_f32_e32 v0, v44, v6
	v_cvt_pk_bf16_f32 v0, v0, s0
	ds_write_b16 v49, v0 offset:54272
	v_mul_f32_e32 v0, v28, v6
	v_cvt_pk_bf16_f32 v0, v0, s0
	v_rcp_f32_e32 v8, v8
	ds_write_b16 v49, v0 offset:54336
	v_mul_f32_e32 v0, v45, v7
	v_cvt_pk_bf16_f32 v0, v0, s0
	ds_write_b16 v49, v0 offset:54400
	v_mul_f32_e32 v0, v29, v7
	v_cvt_pk_bf16_f32 v0, v0, s0
	v_rcp_f32_e32 v9, v9
	ds_write_b16 v49, v0 offset:54464
	v_mul_f32_e32 v0, v46, v8
	v_cvt_pk_bf16_f32 v0, v0, s0
	ds_write_b16 v49, v0 offset:54528
	v_mul_f32_e32 v0, v30, v8
	v_cvt_pk_bf16_f32 v0, v0, s0
	ds_write_b16 v49, v0 offset:54592
	v_mul_f32_e32 v0, v47, v9
	v_cvt_pk_bf16_f32 v0, v0, s0
	ds_write_b16 v49, v0 offset:54656
	v_mul_f32_e32 v0, v31, v9
	v_cvt_pk_bf16_f32 v0, v0, s0
	ds_write_b16 v49, v0 offset:54720
	v_lshlrev_b32_e32 v0, 1, v205
	v_cvt_pk_bf16_f32 v32, v32, s0
	s_add_u32 s6, s6, s63
	v_and_b32_e32 v0, 0x70, v0
	ds_write_b16 v49, v32 offset:51200
	s_addc_u32 s7, s7, 0
	v_lshrrev_b32_e32 v14, 3, v204
	v_add_u32_e32 v15, s8, v0
	s_waitcnt lgkmcnt(0)
	v_lshl_add_u64 v[10:11], s[6:7], 0, v[0:1]
	v_lshl_add_u32 v0, v14, 7, v15
	v_or_b32_e32 v16, 8, v14
	ds_read_b128 v[2:5], v0 offset:51200
	v_lshl_add_u32 v6, v16, 7, v15
	ds_read_b128 v[6:9], v6 offset:51200
	v_lshlrev_b32_e32 v0, 11, v14
	v_lshl_add_u64 v[12:13], v[10:11], 0, v[0:1]
	v_lshlrev_b32_e32 v0, 11, v16
	s_waitcnt lgkmcnt(1)
	global_store_dwordx4 v[12:13], v[2:5], off
	s_nop 1
	v_lshl_add_u64 v[2:3], v[10:11], 0, v[0:1]
	v_or_b32_e32 v0, 16, v14
	s_waitcnt lgkmcnt(0)
	global_store_dwordx4 v[2:3], v[6:9], off
	v_lshl_add_u32 v2, v0, 7, v15
	v_or_b32_e32 v14, 24, v14
	ds_read_b128 v[2:5], v2 offset:51200
	v_lshl_add_u32 v6, v14, 7, v15
	ds_read_b128 v[6:9], v6 offset:51200
	v_lshlrev_b32_e32 v0, 11, v0
	v_lshl_add_u64 v[12:13], v[10:11], 0, v[0:1]
	v_lshlrev_b32_e32 v0, 11, v14
	s_waitcnt lgkmcnt(1)
	global_store_dwordx4 v[12:13], v[2:5], off
	s_nop 1
	v_lshl_add_u64 v[2:3], v[10:11], 0, v[0:1]
	s_waitcnt lgkmcnt(0)
	global_store_dwordx4 v[2:3], v[6:9], off
	s_waitcnt lgkmcnt(0)
	s_barrier
	v_mov_b32_e32 v2, v203
	v_mov_b32_e32 v203, -1
	s_and_saveexec_b64 s[6:7], s[26:27]
	s_cbranch_execz .LBB0_352
	s_mov_b64 s[52:53], exec
	v_mbcnt_lo_u32_b32 v0, s52, 0
	v_mbcnt_hi_u32_b32 v0, s53, v0
	v_cmp_eq_u32_e32 vcc, 0, v0
	s_and_saveexec_b64 s[8:9], vcc
	s_cbranch_execz .LBB0_321
	s_nop 0
	s_nop 0
	s_nop 0
.LBB0_321:
	s_or_b64 exec, exec, s[8:9]
	s_waitcnt vmcnt(4)
	v_readfirstlane_b32 s8, v2
	s_mov_b64 s[52:53], -1
	v_mov_b32_e32 v2, s79
	v_add_u32_e32 v0, s8, v0
	v_cmp_lt_u32_e32 vcc, s87, v0
	s_and_saveexec_b64 s[8:9], vcc
	s_cbranch_execz .LBB0_349
	s_mov_b64 s[54:55], exec
	v_mbcnt_lo_u32_b32 v0, s54, 0
	v_mbcnt_hi_u32_b32 v0, s55, v0
	v_cmp_eq_u32_e32 vcc, 0, v0
	s_and_saveexec_b64 s[52:53], vcc
	s_cbranch_execz .LBB0_324
	s_bcnt1_i32_b64 s10, s[54:55]
	v_mov_b32_e32 v2, s10
	global_atomic_add v2, v1, v2, s[14:15] sc0

.LBB0_352:
	s_or_b64 exec, exec, s[6:7]
	s_and_saveexec_b64 s[6:7], s[26:27]
	s_cbranch_execz .LBB0_317
	v_mov_b32_e32 v0, s68
	ds_write_b32 v0, v203
	s_branch .LBB0_317
